# one static s_setprio 1 for waves 4-7 at kernel entry (younger half), no other setprio
# speedup vs baseline: 1.0025x; 1.0025x over previous
_Z9trunk_fwd4Args:
	v_readfirstlane_b32 s100, v0
	s_nop 3
	s_and_b32 s100, s100, 0x3ff
	s_lshr_b32 s100, s100, 6
	s_cmp_ge_u32 s100, 4
	s_cbranch_scc0 .Lprio_done
	s_setprio 1
.Lprio_done:
	s_load_dwordx8 s[36:43], s[0:1], 0x120
	s_load_dword s97, s[0:1], 0x140
	s_load_dwordx8 s[8:15], s[0:1], 0x100
	s_mov_b32 s4, s2
	s_waitcnt lgkmcnt(0)
	s_mov_b64 s[2:3], s[40:41]
	v_writelane_b32 v250, s8, 0
	s_nop 1
	v_writelane_b32 v250, s9, 1
	v_writelane_b32 v250, s10, 2
	v_writelane_b32 v250, s11, 3
	v_writelane_b32 v250, s12, 4
	v_writelane_b32 v250, s13, 5
	v_writelane_b32 v250, s14, 6
	v_writelane_b32 v250, s15, 7
	v_writelane_b32 v250, s2, 8
	s_nop 1
	v_writelane_b32 v250, s3, 9
	s_add_u32 s2, s0, 0x140
	s_addc_u32 s3, s1, 0
	v_writelane_b32 v250, s2, 10
	s_nop 1
	v_writelane_b32 v250, s3, 11
	s_and_b32 s3, s97, 7
	s_cmp_eq_u32 s3, 0
	s_cselect_b64 s[6:7], -1, 0
	v_writelane_b32 v250, s6, 12
	s_mov_b32 s2, 0
	s_cmp_lg_u32 s3, 0
	v_writelane_b32 v250, s7, 13
	v_writelane_b32 v250, s4, 14
	v_writelane_b32 v250, s4, 15
	s_cbranch_scc1 .LBB0_2
	v_readlane_b32 s6, v250, 14
	s_ashr_i32 s4, s6, 31
	s_lshr_b32 s4, s4, 29
	s_add_i32 s4, s6, s4
	s_ashr_i32 s5, s4, 3
	s_and_b32 s4, s4, -8
	s_ashr_i32 s3, s97, 3
	s_sub_i32 s4, s6, s4
	s_mul_i32 s3, s3, s4
	s_add_i32 s3, s3, s5
	v_writelane_b32 v250, s3, 15
